# NSA prompt units: static s_setprio 1 for waves 4-7 during a unit (7.4) and the SEL-loop ballot trimmed to s_and_b64 -> s_cmp_eq_u64 (7.12)
# speedup vs baseline: 1.0052x; 1.0052x over previous
.LBB0_2269:
	v_mov_b32_e32 v138, v0
	s_cmp_lg_u32 s4, s37
	v_readfirstlane_b32 s84, v138
	s_mov_b64 s[6:7], -1
	s_cbranch_scc0 .LBB0_2283
	s_cmpk_lt_u32 s84, 0x100
	s_cbranch_scc1 .Lmy_p0_lo
	s_setprio 1
.Lmy_p0_lo:
	s_cmp_gt_u32 s4, s37
	s_cselect_b64 s[6:7], -1, 0
	v_cndmask_b32_e64 v1, 0, 1, s[6:7]
	s_mov_b64 s[68:69], s[66:67]
	v_readfirstlane_b32 s5, v1
	s_cmp_eq_u32 s4, s5
	s_cselect_b32 s5, 0, 0x100
	s_add_i32 s5, s5, s40
	s_cmpk_lt_i32 s5, 0x100
	v_readlane_b32 s5, v228, 29
	s_cselect_b32 s65, s41, s5
	s_mov_b32 s5, s36
	v_mov_b32_e32 v91, v0
	s_lshl_b32 s52, s65, 6
	v_readfirstlane_b32 s6, v91
	s_ashr_i32 s28, s6, 6
	s_lshl_b32 s70, s28, 3
	s_add_i32 s6, s70, s52
	v_bfe_u32 v100, v91, 2, 3
	v_or_b32_e32 v96, s6, v100
	v_ashrrev_i32_e32 v97, 31, v96
	v_and_or_b32 v1, v91, 3, s75
	v_lshl_add_u64 v[6:7], s[50:51], 0, v[96:97]
	v_mov_b64_e32 v[2:3], s[68:69]
	s_movk_i32 s8, 0x3000
	v_mad_u64_u32 v[2:3], s[6:7], v6, s8, v[2:3]
	v_mul_u32_u24_e32 v4, 3, v1
	v_mad_i32_i24 v3, v7, s8, v3
	v_lshlrev_b32_e32 v98, 2, v4
	v_lshl_add_u64 v[2:3], v[2:3], 0, v[98:99]
	v_add_co_u32_e32 v2, vcc, 0x16001000, v2
	s_lshl_b32 s29, s28, 13
	s_nop 0
	v_addc_co_u32_e32 v3, vcc, 0, v3, vcc
	global_load_dwordx3 v[2:4], v[2:3], off offset:1024
	v_and_b32_e32 v139, 63, v91
	s_add_i32 s46, s29, 0x9000
	v_and_b32_e32 v114, 31, v91
	v_lshl_or_b32 v5, v139, 2, s46
	v_or_b32_e32 v8, 0xffffffc0, v139
	s_mov_b64 s[6:7], 0

.LBB0_2814:
	s_add_i32 s26, s28, -8
	v_mov_b32_e32 v34, s26
	ds_read_b32 v116, v34
	s_and_b32 s74, s79, 1
	s_waitcnt lgkmcnt(0)
	v_ashrrev_i32_e32 v34, 5, v116
	v_lshl_add_u32 v98, v34, 2, v165
	ds_read_b32 v34, v98
	v_lshlrev_b32_e64 v109, v116, 1
	s_waitcnt lgkmcnt(0)
	v_and_b32_e32 v34, v109, v34
	v_cmp_ne_u32_e32 vcc, 0, v34
	s_cbranch_vccz .LBB0_2823
	s_lshl_b32 s76, s74, 13
	v_add_u32_e32 v117, s76, v167
	ds_read_b128 v[34:37], v117
	ds_read_b128 v[118:121], v117 offset:2048
	ds_read_b128 v[230:233], v117 offset:512
	ds_read_b128 v[234:237], v117 offset:2560
	ds_read_b128 v[238:241], v117 offset:4096
	ds_read_b128 v[242:245], v117 offset:4608
	ds_read_b128 v[246:249], v117 offset:6144
	ds_read_b128 v[250:253], v117 offset:6656
	s_waitcnt lgkmcnt(6)
	v_mfma_f32_32x32x16_bf16 v[50:65], v[34:37], v[66:69], 0
	v_mfma_f32_32x32x16_bf16 v[50:65], v[118:121], v[70:73], v[50:65]
	s_waitcnt lgkmcnt(4)
	v_mfma_f32_32x32x16_bf16 v[34:49], v[230:233], v[66:69], 0
	v_mfma_f32_32x32x16_bf16 v[34:49], v[234:237], v[70:73], v[34:49]
	s_waitcnt lgkmcnt(3)
	v_mfma_f32_32x32x16_bf16 v[50:65], v[238:241], v[74:77], v[50:65]
	s_waitcnt lgkmcnt(2)
	v_mfma_f32_32x32x16_bf16 v[34:49], v[242:245], v[74:77], v[34:49]
	s_waitcnt lgkmcnt(1)
	v_mfma_f32_32x32x16_bf16 v[50:65], v[246:249], v[78:81], v[50:65]
	s_waitcnt lgkmcnt(0)
	v_mfma_f32_32x32x16_bf16 v[34:49], v[250:253], v[78:81], v[34:49]
	v_lshlrev_b32_e32 v116, 6, v116
	ds_read_b32 v117, v98
	v_sub_u32_e32 v98, v116, v96
	v_cvt_f32_i32_e32 v118, v98
	v_sub_u32_e32 v98, v96, v116
	v_cmp_lt_i32_e32 vcc, 62, v98
	s_waitcnt lgkmcnt(0)
	v_and_b32_e32 v109, v117, v109
	v_fma_f32 v116, v90, v118, v164
	v_sub_f32_e32 v171, v116, v168
	v_add_f32_e32 v116, v144, v171
	v_add_f32_e32 v117, v90, v116
	v_pk_add_f32 v[118:119], v[116:117], v[50:51]
	v_pk_add_f32 v[50:51], v[114:115], v[116:117] op_sel_hi:[1,0]
	v_add_f32_e32 v173, v143, v171
	v_pk_add_f32 v[116:117], v[50:51], v[52:53]
	v_add_f32_e32 v50, v111, v171
	v_add_f32_e32 v51, v90, v50
	v_add_f32_e32 v120, v144, v173
	v_pk_add_f32 v[52:53], v[50:51], v[54:55]
	v_pk_add_f32 v[50:51], v[114:115], v[50:51] op_sel_hi:[1,0]
	v_add_f32_e32 v121, v90, v120
	v_pk_add_f32 v[50:51], v[50:51], v[56:57]
	v_pk_add_f32 v[56:57], v[120:121], v[34:35]
	v_add_f32_e32 v34, v91, v120
	v_mov_b32_e32 v121, v173
	v_add_f32_e32 v54, v34, v36
	v_pk_add_f32 v[122:123], v[110:111], v[120:121]
	v_mov_b32_e32 v34, v37
	v_mov_b32_e32 v35, v38
	v_pk_add_f32 v[124:125], v[122:123], v[34:35]
	v_pk_add_f32 v[34:35], v[90:91], v[122:123] op_sel:[0,1]
	v_mov_b32_e32 v36, v39
	v_mov_b32_e32 v37, v40
	v_pk_add_f32 v[120:121], v[34:35], v[36:37]
	v_add_f32_e32 v34, v92, v171
	v_add_f32_e32 v35, v90, v34
	v_pk_add_f32 v[38:39], v[34:35], v[58:59]
	v_pk_add_f32 v[34:35], v[114:115], v[34:35] op_sel_hi:[1,0]
	v_mov_b32_e32 v172, v123
	v_pk_add_f32 v[34:35], v[34:35], v[60:61]
	v_pk_add_f32 v[60:61], v[112:113], v[172:173]
	v_mov_b32_e32 v36, v41
	v_mov_b32_e32 v37, v42
	v_pk_add_f32 v[122:123], v[60:61], v[36:37]
	v_pk_add_f32 v[36:37], v[90:91], v[60:61] op_sel:[0,1]
	v_mov_b32_e32 v40, v43
	v_mov_b32_e32 v41, v44
	v_mov_b32_e32 v172, v61
	v_cmp_ne_u32_e64 s[26:27], 0, v109
	v_pk_add_f32 v[58:59], v[36:37], v[40:41]
	v_add_f32_e32 v36, v103, v171
	v_pk_add_f32 v[42:43], v[102:103], v[172:173]
	v_mov_b32_e32 v44, v45
	v_mov_b32_e32 v45, v46
	s_and_b64 vcc, s[26:27], vcc
	v_add_f32_e32 v37, v90, v36
	v_pk_add_f32 v[60:61], v[42:43], v[44:45]
	v_pk_add_f32 v[44:45], v[90:91], v[42:43] op_sel:[0,1]
	v_add_f32_e32 v42, v110, v43
	v_pk_add_f32 v[40:41], v[36:37], v[62:63]
	v_pk_add_f32 v[36:37], v[114:115], v[36:37] op_sel_hi:[1,0]
	v_mov_b32_e32 v46, v47
	v_mov_b32_e32 v47, v48
	v_pk_add_f32 v[36:37], v[36:37], v[64:65]
	v_pk_add_f32 v[62:63], v[44:45], v[46:47]
	s_cmp_eq_u64 vcc, exec
	v_add_f32_e32 v43, v42, v49
	s_cbranch_scc1 .LBB0_2817
	v_sub_u32_e32 v42, v98, v162
	v_cndmask_b32_e64 v64, v134, v42, s[26:27]
	v_cmp_gt_i32_e32 vcc, 0, v64
	s_or_b64 vcc, s[10:11], vcc
	v_cmp_gt_i32_e64 s[26:27], 40, v64
	v_cndmask_b32_e32 v118, v118, v132, vcc
	v_cmp_gt_i32_e32 vcc, 32, v64
	s_or_b64 vcc, s[16:17], vcc
	s_nop 0
	v_cndmask_b32_e32 v56, v56, v132, vcc
	v_cmp_gt_i32_e32 vcc, 1, v64
	s_or_b64 vcc, s[10:11], vcc
	s_nop 0
	v_cndmask_b32_e32 v119, v119, v132, vcc
	v_cmp_gt_i32_e32 vcc, 33, v64
	s_or_b64 vcc, s[16:17], vcc
	s_nop 0
	v_cndmask_b32_e32 v57, v57, v132, vcc
	v_cmp_gt_i32_e32 vcc, 2, v64
	s_or_b64 vcc, s[10:11], vcc
	s_nop 0
	v_cndmask_b32_e32 v116, v116, v132, vcc
	v_cmp_gt_i32_e32 vcc, 34, v64
	s_or_b64 vcc, s[16:17], vcc
	s_nop 0
	v_cndmask_b32_e32 v54, v54, v132, vcc
	v_cmp_gt_i32_e32 vcc, 3, v64
	s_or_b64 vcc, s[10:11], vcc
	s_nop 0
	v_cndmask_b32_e32 v117, v117, v132, vcc
	v_cmp_gt_i32_e32 vcc, 8, v64
	s_or_b64 vcc, s[12:13], vcc
	s_nop 0
	v_cndmask_b32_e32 v52, v52, v132, vcc
	v_cmp_gt_i32_e32 vcc, 35, v64
	s_or_b64 vcc, s[16:17], vcc
	s_nop 0
	v_cndmask_b32_e32 v55, v124, v132, vcc
	s_or_b64 vcc, s[14:15], s[26:27]
	v_cndmask_b32_e32 v44, v125, v132, vcc
	v_cmp_gt_i32_e32 vcc, 9, v64
	s_or_b64 vcc, s[12:13], vcc
	s_nop 0
	v_cndmask_b32_e32 v53, v53, v132, vcc
	v_cmp_gt_i32_e32 vcc, 41, v64
	s_or_b64 vcc, s[14:15], vcc
	s_nop 0
	v_cndmask_b32_e32 v45, v120, v132, vcc
	v_cmp_gt_i32_e32 vcc, 10, v64
	s_or_b64 vcc, s[12:13], vcc
	s_nop 0
	v_cndmask_b32_e32 v50, v50, v132, vcc
	v_cmp_gt_i32_e32 vcc, 42, v64
	s_or_b64 vcc, s[14:15], vcc
	s_nop 0
	v_cndmask_b32_e32 v46, v121, v132, vcc
	v_cmp_gt_i32_e32 vcc, 11, v64
	s_or_b64 vcc, s[12:13], vcc
	s_nop 0
	v_cndmask_b32_e32 v51, v51, v132, vcc
	v_cmp_gt_i32_e32 vcc, 43, v64
	s_or_b64 vcc, s[14:15], vcc
	s_nop 0
	v_cndmask_b32_e32 v47, v122, v132, vcc
	v_cmp_gt_i32_e32 vcc, 16, v64
	s_or_b64 vcc, s[18:19], vcc
	s_nop 0
	v_cndmask_b32_e32 v38, v38, v132, vcc
	v_cmp_gt_i32_e32 vcc, 48, v64
	s_or_b64 vcc, s[20:21], vcc
	s_nop 0
	v_cndmask_b32_e32 v48, v123, v132, vcc
	v_cmp_gt_i32_e32 vcc, 17, v64
	s_or_b64 vcc, s[18:19], vcc
	s_nop 0
	v_cndmask_b32_e32 v39, v39, v132, vcc
	v_cmp_gt_i32_e32 vcc, 49, v64
	s_or_b64 vcc, s[20:21], vcc
	s_nop 0
	v_cndmask_b32_e32 v49, v58, v132, vcc
	v_cmp_gt_i32_e32 vcc, 18, v64
	s_or_b64 vcc, s[18:19], vcc
	s_nop 0
	v_cndmask_b32_e32 v34, v34, v132, vcc
	v_cmp_gt_i32_e32 vcc, 50, v64
	s_or_b64 vcc, s[20:21], vcc
	s_nop 0
	v_cndmask_b32_e32 v58, v59, v132, vcc
	v_cmp_gt_i32_e32 vcc, 19, v64
	s_or_b64 vcc, s[18:19], vcc
	s_nop 0
	v_cndmask_b32_e32 v35, v35, v132, vcc
	v_cmp_gt_i32_e32 vcc, 51, v64
	s_or_b64 vcc, s[20:21], vcc
	s_nop 0
	v_cndmask_b32_e32 v59, v60, v132, vcc
	v_cmp_gt_i32_e32 vcc, 24, v64
	s_or_b64 vcc, s[22:23], vcc
	s_nop 0
	v_cndmask_b32_e32 v40, v40, v132, vcc
	v_cmp_gt_i32_e32 vcc, 56, v64
	s_or_b64 vcc, s[24:25], vcc
	s_nop 0
	v_cndmask_b32_e32 v60, v61, v132, vcc
	v_cmp_gt_i32_e32 vcc, 25, v64
	s_or_b64 vcc, s[22:23], vcc
	s_nop 0
	v_cndmask_b32_e32 v41, v41, v132, vcc
	v_cmp_gt_i32_e32 vcc, 57, v64
	s_or_b64 vcc, s[24:25], vcc
	s_nop 0
	v_cndmask_b32_e32 v61, v62, v132, vcc
	v_cmp_gt_i32_e32 vcc, 26, v64
	s_or_b64 vcc, s[22:23], vcc
	s_nop 0
	v_cndmask_b32_e32 v36, v36, v132, vcc
	v_cmp_gt_i32_e32 vcc, 58, v64
	s_or_b64 vcc, s[24:25], vcc
	s_nop 0
	v_cndmask_b32_e32 v42, v63, v132, vcc
	v_cmp_gt_i32_e32 vcc, 27, v64
	s_or_b64 vcc, s[22:23], vcc
	s_nop 0
	v_cndmask_b32_e32 v37, v37, v132, vcc
	v_cmp_gt_i32_e32 vcc, 59, v64
	s_or_b64 vcc, s[24:25], vcc
	s_nop 0
	v_cndmask_b32_e32 v43, v43, v132, vcc
	s_branch .LBB0_2818

.LBB0_2895:
	s_setprio 0
	s_add_i32 s4, s4, 1
	s_cmp_eq_u32 s4, 3
	s_cbranch_scc1 .LBB0_2898

.LBB0_4876:
	v_mov_b32_e32 v138, v0
	s_cmp_eq_u32 s4, s74
	v_readfirstlane_b32 s86, v138
	s_mov_b64 s[6:7], -1
	s_cbranch_scc1 .LBB0_4890
	s_cmpk_lt_u32 s86, 0x100
	s_cbranch_scc1 .Lmy_p1_lo
	s_setprio 1
.Lmy_p1_lo:
	s_cmp_gt_u32 s4, s74
	s_cselect_b64 s[6:7], -1, 0
	v_cndmask_b32_e64 v1, 0, 1, s[6:7]
	s_mov_b64 s[68:69], s[66:67]
	v_readfirstlane_b32 s5, v1
	s_cmp_eq_u32 s4, s5
	s_cselect_b32 s5, 0, 0x100
	s_add_i32 s5, s5, s40
	s_cmpk_lt_i32 s5, 0x100
	s_mov_b32 s5, s3
	v_mov_b32_e32 v91, v0
	s_cselect_b32 s65, s75, s76
	v_readfirstlane_b32 s6, v91
	s_ashr_i32 s28, s6, 6
	s_lshl_b32 s52, s65, 6
	s_lshl_b32 s70, s28, 3
	s_add_i32 s6, s70, s52
	v_bfe_u32 v100, v91, 2, 3
	v_or_b32_e32 v96, s6, v100
	v_ashrrev_i32_e32 v97, 31, v96
	v_and_or_b32 v1, v91, 3, s77
	v_lshl_add_u64 v[6:7], s[50:51], 0, v[96:97]
	v_mov_b64_e32 v[2:3], s[68:69]
	s_movk_i32 s8, 0x3000
	v_mad_u64_u32 v[2:3], s[6:7], v6, s8, v[2:3]
	v_mul_u32_u24_e32 v4, 3, v1
	v_mad_i32_i24 v3, v7, s8, v3
	v_lshlrev_b32_e32 v98, 2, v4
	v_lshl_add_u64 v[2:3], v[2:3], 0, v[98:99]
	v_add_co_u32_e32 v2, vcc, 0x16001000, v2
	s_lshl_b32 s29, s28, 13
	s_nop 0
	v_addc_co_u32_e32 v3, vcc, 0, v3, vcc
	global_load_dwordx3 v[2:4], v[2:3], off offset:1024
	v_and_b32_e32 v139, 63, v91
	s_add_i32 s42, s29, 0x9000
	v_and_b32_e32 v114, 31, v91
	v_lshl_or_b32 v5, v139, 2, s42
	v_or_b32_e32 v8, 0xffffffc0, v139
	s_mov_b64 s[6:7], 0

.LBB0_5427:
	s_add_i32 s26, s28, -8
	v_mov_b32_e32 v34, s26
	ds_read_b32 v116, v34
	s_and_b32 s47, s46, 1
	s_waitcnt lgkmcnt(0)
	v_ashrrev_i32_e32 v34, 5, v116
	v_lshl_add_u32 v98, v34, 2, v165
	ds_read_b32 v34, v98
	v_lshlrev_b32_e64 v109, v116, 1
	s_waitcnt lgkmcnt(0)
	v_and_b32_e32 v34, v109, v34
	v_cmp_ne_u32_e32 vcc, 0, v34
	s_cbranch_vccz .LBB0_5436
	s_lshl_b32 s81, s47, 13
	v_add_u32_e32 v117, s81, v167
	ds_read_b128 v[34:37], v117
	ds_read_b128 v[118:121], v117 offset:2048
	ds_read_b128 v[230:233], v117 offset:512
	ds_read_b128 v[234:237], v117 offset:2560
	ds_read_b128 v[238:241], v117 offset:4096
	ds_read_b128 v[242:245], v117 offset:4608
	ds_read_b128 v[246:249], v117 offset:6144
	ds_read_b128 v[250:253], v117 offset:6656
	s_waitcnt lgkmcnt(6)
	v_mfma_f32_32x32x16_bf16 v[50:65], v[34:37], v[66:69], 0
	v_mfma_f32_32x32x16_bf16 v[50:65], v[118:121], v[70:73], v[50:65]
	s_waitcnt lgkmcnt(4)
	v_mfma_f32_32x32x16_bf16 v[34:49], v[230:233], v[66:69], 0
	v_mfma_f32_32x32x16_bf16 v[34:49], v[234:237], v[70:73], v[34:49]
	s_waitcnt lgkmcnt(3)
	v_mfma_f32_32x32x16_bf16 v[50:65], v[238:241], v[74:77], v[50:65]
	s_waitcnt lgkmcnt(2)
	v_mfma_f32_32x32x16_bf16 v[34:49], v[242:245], v[74:77], v[34:49]
	s_waitcnt lgkmcnt(1)
	v_mfma_f32_32x32x16_bf16 v[50:65], v[246:249], v[78:81], v[50:65]
	s_waitcnt lgkmcnt(0)
	v_mfma_f32_32x32x16_bf16 v[34:49], v[250:253], v[78:81], v[34:49]
	v_lshlrev_b32_e32 v116, 6, v116
	ds_read_b32 v117, v98
	v_sub_u32_e32 v98, v116, v96
	v_cvt_f32_i32_e32 v118, v98
	v_sub_u32_e32 v98, v96, v116
	v_cmp_lt_i32_e32 vcc, 62, v98
	s_waitcnt lgkmcnt(0)
	v_and_b32_e32 v109, v117, v109
	v_fma_f32 v116, v90, v118, v164
	v_sub_f32_e32 v171, v116, v168
	v_add_f32_e32 v116, v144, v171
	v_add_f32_e32 v117, v90, v116
	v_pk_add_f32 v[118:119], v[116:117], v[50:51]
	v_pk_add_f32 v[50:51], v[114:115], v[116:117] op_sel_hi:[1,0]
	v_add_f32_e32 v173, v143, v171
	v_pk_add_f32 v[116:117], v[50:51], v[52:53]
	v_add_f32_e32 v50, v111, v171
	v_add_f32_e32 v51, v90, v50
	v_add_f32_e32 v120, v144, v173
	v_pk_add_f32 v[52:53], v[50:51], v[54:55]
	v_pk_add_f32 v[50:51], v[114:115], v[50:51] op_sel_hi:[1,0]
	v_add_f32_e32 v121, v90, v120
	v_pk_add_f32 v[50:51], v[50:51], v[56:57]
	v_pk_add_f32 v[56:57], v[120:121], v[34:35]
	v_add_f32_e32 v34, v91, v120
	v_mov_b32_e32 v121, v173
	v_add_f32_e32 v54, v34, v36
	v_pk_add_f32 v[122:123], v[110:111], v[120:121]
	v_mov_b32_e32 v34, v37
	v_mov_b32_e32 v35, v38
	v_pk_add_f32 v[124:125], v[122:123], v[34:35]
	v_pk_add_f32 v[34:35], v[90:91], v[122:123] op_sel:[0,1]
	v_mov_b32_e32 v36, v39
	v_mov_b32_e32 v37, v40
	v_pk_add_f32 v[120:121], v[34:35], v[36:37]
	v_add_f32_e32 v34, v92, v171
	v_add_f32_e32 v35, v90, v34
	v_pk_add_f32 v[38:39], v[34:35], v[58:59]
	v_pk_add_f32 v[34:35], v[114:115], v[34:35] op_sel_hi:[1,0]
	v_mov_b32_e32 v172, v123
	v_pk_add_f32 v[34:35], v[34:35], v[60:61]
	v_pk_add_f32 v[60:61], v[112:113], v[172:173]
	v_mov_b32_e32 v36, v41
	v_mov_b32_e32 v37, v42
	v_pk_add_f32 v[122:123], v[60:61], v[36:37]
	v_pk_add_f32 v[36:37], v[90:91], v[60:61] op_sel:[0,1]
	v_mov_b32_e32 v40, v43
	v_mov_b32_e32 v41, v44
	v_mov_b32_e32 v172, v61
	v_cmp_ne_u32_e64 s[26:27], 0, v109
	v_pk_add_f32 v[58:59], v[36:37], v[40:41]
	v_add_f32_e32 v36, v103, v171
	v_pk_add_f32 v[42:43], v[102:103], v[172:173]
	v_mov_b32_e32 v44, v45
	v_mov_b32_e32 v45, v46
	s_and_b64 vcc, s[26:27], vcc
	v_add_f32_e32 v37, v90, v36
	v_pk_add_f32 v[60:61], v[42:43], v[44:45]
	v_pk_add_f32 v[44:45], v[90:91], v[42:43] op_sel:[0,1]
	v_add_f32_e32 v42, v110, v43
	v_pk_add_f32 v[40:41], v[36:37], v[62:63]
	v_pk_add_f32 v[36:37], v[114:115], v[36:37] op_sel_hi:[1,0]
	v_mov_b32_e32 v46, v47
	v_mov_b32_e32 v47, v48
	v_pk_add_f32 v[36:37], v[36:37], v[64:65]
	v_pk_add_f32 v[62:63], v[44:45], v[46:47]
	s_cmp_eq_u64 vcc, exec
	v_add_f32_e32 v43, v42, v49
	s_cbranch_scc1 .LBB0_5430
	v_sub_u32_e32 v42, v98, v162
	v_cndmask_b32_e64 v64, v134, v42, s[26:27]
	v_cmp_gt_i32_e32 vcc, 0, v64
	s_or_b64 vcc, s[10:11], vcc
	v_cmp_gt_i32_e64 s[26:27], 40, v64
	v_cndmask_b32_e32 v118, v118, v132, vcc
	v_cmp_gt_i32_e32 vcc, 32, v64
	s_or_b64 vcc, s[16:17], vcc
	s_nop 0
	v_cndmask_b32_e32 v56, v56, v132, vcc
	v_cmp_gt_i32_e32 vcc, 1, v64
	s_or_b64 vcc, s[10:11], vcc
	s_nop 0
	v_cndmask_b32_e32 v119, v119, v132, vcc
	v_cmp_gt_i32_e32 vcc, 33, v64
	s_or_b64 vcc, s[16:17], vcc
	s_nop 0
	v_cndmask_b32_e32 v57, v57, v132, vcc
	v_cmp_gt_i32_e32 vcc, 2, v64
	s_or_b64 vcc, s[10:11], vcc
	s_nop 0
	v_cndmask_b32_e32 v116, v116, v132, vcc
	v_cmp_gt_i32_e32 vcc, 34, v64
	s_or_b64 vcc, s[16:17], vcc
	s_nop 0
	v_cndmask_b32_e32 v54, v54, v132, vcc
	v_cmp_gt_i32_e32 vcc, 3, v64
	s_or_b64 vcc, s[10:11], vcc
	s_nop 0
	v_cndmask_b32_e32 v117, v117, v132, vcc
	v_cmp_gt_i32_e32 vcc, 8, v64
	s_or_b64 vcc, s[12:13], vcc
	s_nop 0
	v_cndmask_b32_e32 v52, v52, v132, vcc
	v_cmp_gt_i32_e32 vcc, 35, v64
	s_or_b64 vcc, s[16:17], vcc
	s_nop 0
	v_cndmask_b32_e32 v55, v124, v132, vcc
	s_or_b64 vcc, s[14:15], s[26:27]
	v_cndmask_b32_e32 v44, v125, v132, vcc
	v_cmp_gt_i32_e32 vcc, 9, v64
	s_or_b64 vcc, s[12:13], vcc
	s_nop 0
	v_cndmask_b32_e32 v53, v53, v132, vcc
	v_cmp_gt_i32_e32 vcc, 41, v64
	s_or_b64 vcc, s[14:15], vcc
	s_nop 0
	v_cndmask_b32_e32 v45, v120, v132, vcc
	v_cmp_gt_i32_e32 vcc, 10, v64
	s_or_b64 vcc, s[12:13], vcc
	s_nop 0
	v_cndmask_b32_e32 v50, v50, v132, vcc
	v_cmp_gt_i32_e32 vcc, 42, v64
	s_or_b64 vcc, s[14:15], vcc
	s_nop 0
	v_cndmask_b32_e32 v46, v121, v132, vcc
	v_cmp_gt_i32_e32 vcc, 11, v64
	s_or_b64 vcc, s[12:13], vcc
	s_nop 0
	v_cndmask_b32_e32 v51, v51, v132, vcc
	v_cmp_gt_i32_e32 vcc, 43, v64
	s_or_b64 vcc, s[14:15], vcc
	s_nop 0
	v_cndmask_b32_e32 v47, v122, v132, vcc
	v_cmp_gt_i32_e32 vcc, 16, v64
	s_or_b64 vcc, s[18:19], vcc
	s_nop 0
	v_cndmask_b32_e32 v38, v38, v132, vcc
	v_cmp_gt_i32_e32 vcc, 48, v64
	s_or_b64 vcc, s[20:21], vcc
	s_nop 0
	v_cndmask_b32_e32 v48, v123, v132, vcc
	v_cmp_gt_i32_e32 vcc, 17, v64
	s_or_b64 vcc, s[18:19], vcc
	s_nop 0
	v_cndmask_b32_e32 v39, v39, v132, vcc
	v_cmp_gt_i32_e32 vcc, 49, v64
	s_or_b64 vcc, s[20:21], vcc
	s_nop 0
	v_cndmask_b32_e32 v49, v58, v132, vcc
	v_cmp_gt_i32_e32 vcc, 18, v64
	s_or_b64 vcc, s[18:19], vcc
	s_nop 0
	v_cndmask_b32_e32 v34, v34, v132, vcc
	v_cmp_gt_i32_e32 vcc, 50, v64
	s_or_b64 vcc, s[20:21], vcc
	s_nop 0
	v_cndmask_b32_e32 v58, v59, v132, vcc
	v_cmp_gt_i32_e32 vcc, 19, v64
	s_or_b64 vcc, s[18:19], vcc
	s_nop 0
	v_cndmask_b32_e32 v35, v35, v132, vcc
	v_cmp_gt_i32_e32 vcc, 51, v64
	s_or_b64 vcc, s[20:21], vcc
	s_nop 0
	v_cndmask_b32_e32 v59, v60, v132, vcc
	v_cmp_gt_i32_e32 vcc, 24, v64
	s_or_b64 vcc, s[22:23], vcc
	s_nop 0
	v_cndmask_b32_e32 v40, v40, v132, vcc
	v_cmp_gt_i32_e32 vcc, 56, v64
	s_or_b64 vcc, s[24:25], vcc
	s_nop 0
	v_cndmask_b32_e32 v60, v61, v132, vcc
	v_cmp_gt_i32_e32 vcc, 25, v64
	s_or_b64 vcc, s[22:23], vcc
	s_nop 0
	v_cndmask_b32_e32 v41, v41, v132, vcc
	v_cmp_gt_i32_e32 vcc, 57, v64
	s_or_b64 vcc, s[24:25], vcc
	s_nop 0
	v_cndmask_b32_e32 v61, v62, v132, vcc
	v_cmp_gt_i32_e32 vcc, 26, v64
	s_or_b64 vcc, s[22:23], vcc
	s_nop 0
	v_cndmask_b32_e32 v36, v36, v132, vcc
	v_cmp_gt_i32_e32 vcc, 58, v64
	s_or_b64 vcc, s[24:25], vcc
	s_nop 0
	v_cndmask_b32_e32 v42, v63, v132, vcc
	v_cmp_gt_i32_e32 vcc, 27, v64
	s_or_b64 vcc, s[22:23], vcc
	s_nop 0
	v_cndmask_b32_e32 v37, v37, v132, vcc
	v_cmp_gt_i32_e32 vcc, 59, v64
	s_or_b64 vcc, s[24:25], vcc
	s_nop 0
	v_cndmask_b32_e32 v43, v43, v132, vcc
	s_branch .LBB0_5431

.LBB0_5502:
	s_setprio 0
	s_add_i32 s4, s4, 1
	s_cmp_lg_u32 s4, 3
	s_cbranch_scc0 .LBB0_5505
